# attention loop: V LDS reads interleaved into QK / PV MFMA chains with counted lgkmcnt waits; 10 exps issued early in the PV c0c1 block
# baseline (speedup 1.0000x reference)
; #define SB() __builtin_amdgcn_sched_barrier(0)
; #define ATT_QKM(t) do { _Pragma("unroll") for (int kb = 0; kb < 2; ++kb) _Pragma("unroll") for (int i = 0; i < 16; ++i) p[kb][i] = cinit_; \
;         SB(); __builtin_amdgcn_s_setprio(1); \
;         _Pragma("unroll") for (int s_ = 0; s_ < 4; ++s_) _Pragma("unroll") for (int kb = 0; kb < 2; ++kb) p[kb] = MFMA32(kf[kb * 4 + s_], qf[s_], p[kb]); \
;         __builtin_amdgcn_s_setprio(0); SB(); } while (0)
; #define ATT_LWAIT() asm volatile("s_waitcnt lgkmcnt(0)" ::: "memory")
; #define ATT_VRD(dst, c) do { const unsigned va_ = vaddr_ + 64u * (unsigned)((c) ^ vq); \
;         ATT_TR(dst[0], va_, 0);     ATT_TR(dst[1], va_, 2048);  ATT_TR(dst[2], va_, 4096);  ATT_TR(dst[3], va_, 6144); \
;         ATT_TR(dst[4], va_, 8192);  ATT_TR(dst[5], va_, 10240); ATT_TR(dst[6], va_, 12288); ATT_TR(dst[7], va_, 14336); } while (0)
; __device__ __forceinline__ void attn_item(CP& P, int L, int sq, int hh, int qt, float lam, float lam_init, LAS unsigned char* lds) {
;     ...
;         const int k0_ = t * 64; const bool farR_ = (k0_ - (q0w + 31) >= 128), farL_ = (q0w - (k0_ + 63) >= 128); far_ = farR_ || farL_;
;         const float cinit_ = (far_ ? (farR_ ? tbl[256] : tbl[0]) : 0.f) - mref;
;         if (t > 0) {
;             const unsigned vaddr_ = (unsigned)(size_t)(lds + ((t - 1) & 3) * A_SLOT + vfo); s16x4 va0_[8], va1_[8];
;             ATT_VRD(va0_, 0); ATT_VRD(va1_, 1); ATT_LWAIT(); SB();
;             ATT_VMM2(va0_, 0, va1_, 1); SB();
;             ATT_VRD(va0_, 2); ATT_VRD(va1_, 3); ATT_LWAIT(); ATT_KRD(t & 3); SB();
;             ATT_VMM2(va0_, 2, va1_, 3); SB(); ATT_LWAIT(); SB();
;         } else { ATT_KRD(0); ATT_LWAIT(); SB(); }
;         ATT_QKM(t);
.LBB0_72:
	s_and_b32 s5, s20, 0x18000
	s_add_i32 s4, s20, 0xfffe8000
	s_and_b32 s4, s4, 0x18000
	v_add_u32_e32 v65, s4, v134
	v_add_u32_e32 v94, v130, v65
	ds_read_b128 v[162:165], v94
	ds_read_b128 v[166:169], v94 offset:4096
	v_add_u32_e32 v94, v131, v65
	ds_read_b128 v[170:173], v94
	ds_read_b128 v[174:177], v94 offset:4096
	v_add_u32_e32 v94, v132, v65
	ds_read_b128 v[178:181], v94
	ds_read_b128 v[182:185], v94 offset:4096
	v_add_u32_e32 v65, v133, v65
	ds_read_b128 v[186:189], v65
	ds_read_b128 v[200:203], v65 offset:4096
	v_add_u32_e32 v224, s5, v140
	v_add_u32_e32 v224, 0x4000, v224
	v_add_u32_e32 v225, v139, v224
	v_add_u32_e32 v226, v137, v224
	v_add_u32_e32 v242, v136, v224
	v_add_u32_e32 v243, v135, v224
	s_waitcnt lgkmcnt(8)
	v_sub_f32_e32 v64, v64, v124
	v_mov_b32_e32 v65, v64
	v_mov_b32_e32 v66, v64
	v_mov_b32_e32 v67, v64
	v_mov_b32_e32 v68, v64
	v_mov_b32_e32 v69, v64
	v_mov_b32_e32 v70, v64
	v_mov_b32_e32 v71, v64
	v_mov_b32_e32 v72, v64
	v_mov_b32_e32 v73, v64
	v_mov_b32_e32 v74, v64
	v_mov_b32_e32 v75, v64
	v_mov_b32_e32 v76, v64
	v_mov_b32_e32 v77, v64
	v_mov_b32_e32 v78, v64
	v_mov_b32_e32 v79, v64
	s_setprio 1
	s_nop 0
	s_waitcnt lgkmcnt(7)
	v_mfma_f32_32x32x16_bf16 v[80:95], v[162:165], v[96:99], v[64:79]
	ds_read_b64_tr_b16 v[162:163], v225 offset:0
	ds_read_b64_tr_b16 v[164:165], v225 offset:2048
	s_waitcnt lgkmcnt(8)
	v_mfma_f32_32x32x16_bf16 v[64:79], v[166:169], v[96:99], v[64:79]
	ds_read_b64_tr_b16 v[166:167], v225 offset:4096
	ds_read_b64_tr_b16 v[168:169], v225 offset:6144
	s_waitcnt lgkmcnt(9)
	v_mfma_f32_32x32x16_bf16 v[80:95], v[170:173], v[100:103], v[80:95]
	ds_read_b64_tr_b16 v[170:171], v225 offset:8192
	ds_read_b64_tr_b16 v[172:173], v225 offset:10240
	s_waitcnt lgkmcnt(10)
	v_mfma_f32_32x32x16_bf16 v[64:79], v[174:177], v[100:103], v[64:79]
	ds_read_b64_tr_b16 v[174:175], v225 offset:12288
	ds_read_b64_tr_b16 v[176:177], v225 offset:14336
	s_waitcnt lgkmcnt(11)
	v_mfma_f32_32x32x16_bf16 v[80:95], v[178:181], v[104:107], v[80:95]
	ds_read_b64_tr_b16 v[178:179], v226 offset:0
	ds_read_b64_tr_b16 v[180:181], v226 offset:2048
	s_waitcnt lgkmcnt(12)
	v_mfma_f32_32x32x16_bf16 v[64:79], v[182:185], v[104:107], v[64:79]
	ds_read_b64_tr_b16 v[182:183], v226 offset:4096
	ds_read_b64_tr_b16 v[184:185], v226 offset:6144
	s_waitcnt lgkmcnt(13)
	v_mfma_f32_32x32x16_bf16 v[80:95], v[186:189], v[108:111], v[80:95]
	ds_read_b64_tr_b16 v[186:187], v226 offset:8192
	ds_read_b64_tr_b16 v[188:189], v226 offset:10240
	s_waitcnt lgkmcnt(13)
	v_mfma_f32_32x32x16_bf16 v[64:79], v[200:203], v[108:111], v[64:79]
	ds_read_b64_tr_b16 v[200:201], v226 offset:12288
	ds_read_b64_tr_b16 v[202:203], v226 offset:14336
	s_setprio 0
	s_andn2_b64 vcc, exec, s[0:1]
	s_cbranch_vccnz .LBB0_74
	s_waitcnt lgkmcnt(0)
	v_add_u32_e32 v158, s14, v141
	v_mov_b32_e32 v142, 0x80
	s_movk_i32 s0, 0xff80
	v_med3_i32 v142, v158, s0, v142
	s_add_i32 s0, 0, 0x20000
	v_lshl_add_u32 v150, v142, 2, s0
	v_mov_b32_e32 v142, 0x7f
	s_movk_i32 s1, 0xff7f
	v_med3_i32 v142, v158, s1, v142
	v_lshl_add_u32 v151, v142, 2, s0
	v_mov_b32_e32 v142, 0x7e
	s_movk_i32 s1, 0xff7e
	v_med3_i32 v142, v158, s1, v142
	v_lshl_add_u32 v152, v142, 2, s0
	v_mov_b32_e32 v142, 0x7d
	s_movk_i32 s1, 0xff7d
	v_med3_i32 v142, v158, s1, v142
	v_lshl_add_u32 v153, v142, 2, s0
	v_mov_b32_e32 v142, 0x78
	s_movk_i32 s1, 0xff78
	v_med3_i32 v142, v158, s1, v142
	v_lshl_add_u32 v154, v142, 2, s0
	v_mov_b32_e32 v142, 0x77
	s_movk_i32 s1, 0xff77
	v_med3_i32 v142, v158, s1, v142
	v_lshl_add_u32 v155, v142, 2, s0
	v_mov_b32_e32 v142, 0x76
	s_movk_i32 s1, 0xff76
	v_med3_i32 v142, v158, s1, v142
	v_lshl_add_u32 v156, v142, 2, s0
	v_mov_b32_e32 v142, 0x75
	s_movk_i32 s1, 0xff75
	v_med3_i32 v142, v158, s1, v142
	v_lshl_add_u32 v157, v142, 2, s0
	v_mov_b32_e32 v142, 0x70
	s_movk_i32 s1, 0xff70
	v_med3_i32 v142, v158, s1, v142
	v_mov_b32_e32 v143, 0x6f
	s_movk_i32 s1, 0xff6f
	v_med3_i32 v143, v158, s1, v143
	v_mov_b32_e32 v144, 0x6e
	s_movk_i32 s1, 0xff6e
	v_med3_i32 v144, v158, s1, v144
	v_mov_b32_e32 v145, 0x6d
	s_movk_i32 s1, 0xff6d
	v_med3_i32 v145, v158, s1, v145
	v_mov_b32_e32 v146, 0x68
	s_movk_i32 s1, 0xff68
	v_med3_i32 v146, v158, s1, v146
	v_mov_b32_e32 v147, 0x67
	s_movk_i32 s1, 0xff67
	v_med3_i32 v147, v158, s1, v147
	v_mov_b32_e32 v148, 0x66
	s_movk_i32 s1, 0xff66
	v_med3_i32 v148, v158, s1, v148
	v_mov_b32_e32 v149, 0x65
	s_movk_i32 s1, 0xff65
	v_med3_i32 v149, v158, s1, v149
	v_lshl_add_u32 v142, v142, 2, s0
	v_lshl_add_u32 v143, v143, 2, s0
	v_lshl_add_u32 v144, v144, 2, s0
	v_lshl_add_u32 v145, v145, 2, s0
	v_lshl_add_u32 v146, v146, 2, s0
	v_lshl_add_u32 v147, v147, 2, s0
	v_lshl_add_u32 v148, v148, 2, s0
	v_lshl_add_u32 v149, v149, 2, s0
	ds_read_b32 v142, v142 offset:576
	ds_read_b32 v143, v143 offset:580
	ds_read_b32 v144, v144 offset:584
	ds_read_b32 v145, v145 offset:588
	ds_read_b32 v146, v146 offset:608
	ds_read_b32 v147, v147 offset:612
	ds_read_b32 v148, v148 offset:616
	ds_read_b32 v149, v149 offset:620
	ds_read_b32 v150, v150 offset:512
	ds_read_b32 v151, v151 offset:516
	ds_read_b32 v152, v152 offset:520
	ds_read_b32 v153, v153 offset:524
	ds_read_b32 v154, v154 offset:544
	ds_read_b32 v155, v155 offset:548
	ds_read_b32 v156, v156 offset:552
	ds_read_b32 v157, v157 offset:556
	s_waitcnt lgkmcnt(0)
	v_pk_add_f32 v[88:89], v[88:89], v[142:143]
	v_mov_b32_e32 v142, 0x60
	s_movk_i32 s1, 0xff60
	v_med3_i32 v142, v158, s1, v142
	v_pk_add_f32 v[80:81], v[80:81], v[150:151]
	v_lshl_add_u32 v150, v142, 2, s0
	v_mov_b32_e32 v142, 0x5f
	s_movk_i32 s1, 0xff5f
	v_med3_i32 v142, v158, s1, v142
	v_lshl_add_u32 v151, v142, 2, s0
	v_mov_b32_e32 v142, 0x5e
	s_movk_i32 s1, 0xff5e
	v_med3_i32 v142, v158, s1, v142
	v_pk_add_f32 v[82:83], v[82:83], v[152:153]
	v_lshl_add_u32 v152, v142, 2, s0
	v_mov_b32_e32 v142, 0x5d
	s_movk_i32 s1, 0xff5d
	v_med3_i32 v142, v158, s1, v142
	v_lshl_add_u32 v153, v142, 2, s0
	v_mov_b32_e32 v142, 0x58
	s_movk_i32 s1, 0xff58
	v_med3_i32 v142, v158, s1, v142
	v_pk_add_f32 v[84:85], v[84:85], v[154:155]
	v_lshl_add_u32 v154, v142, 2, s0
	v_mov_b32_e32 v142, 0x57
	s_movk_i32 s1, 0xff57
	v_med3_i32 v142, v158, s1, v142
	v_lshl_add_u32 v155, v142, 2, s0
	v_mov_b32_e32 v142, 0x56
	s_movk_i32 s1, 0xff56
	v_med3_i32 v142, v158, s1, v142
	v_pk_add_f32 v[86:87], v[86:87], v[156:157]
	v_lshl_add_u32 v156, v142, 2, s0
	v_mov_b32_e32 v142, 0x55
	s_movk_i32 s1, 0xff55
	v_med3_i32 v142, v158, s1, v142
	v_lshl_add_u32 v157, v142, 2, s0
	v_mov_b32_e32 v142, 0x50
	s_movk_i32 s1, 0xff50
	v_med3_i32 v142, v158, s1, v142
	v_mov_b32_e32 v143, 0x4f
	s_movk_i32 s1, 0xff4f
	v_pk_add_f32 v[90:91], v[90:91], v[144:145]
	v_med3_i32 v143, v158, s1, v143
	v_mov_b32_e32 v144, 0x4e
	s_movk_i32 s1, 0xff4e
	v_med3_i32 v144, v158, s1, v144
	s_movk_i32 s1, 0xff4d
	v_med3_i32 v145, v158, s1, v232
	s_movk_i32 s1, 0xff48
	v_pk_add_f32 v[92:93], v[92:93], v[146:147]
	v_med3_i32 v146, v158, s1, v233
	s_movk_i32 s1, 0xff47
	v_med3_i32 v147, v158, s1, v234
	s_movk_i32 s1, 0xff46
	v_pk_add_f32 v[94:95], v[94:95], v[148:149]
	v_med3_i32 v148, v158, s1, v235
	s_movk_i32 s1, 0xff45
	v_med3_i32 v149, v158, s1, v236
	v_lshl_add_u32 v142, v142, 2, s0
	v_lshl_add_u32 v143, v143, 2, s0
	v_lshl_add_u32 v144, v144, 2, s0
	v_lshl_add_u32 v145, v145, 2, s0
	v_lshl_add_u32 v146, v146, 2, s0
	v_lshl_add_u32 v147, v147, 2, s0
	v_lshl_add_u32 v148, v148, 2, s0
	v_lshl_add_u32 v149, v149, 2, s0
	ds_read_b32 v142, v142 offset:704
	ds_read_b32 v143, v143 offset:708
	ds_read_b32 v144, v144 offset:712
	ds_read_b32 v145, v145 offset:716
	ds_read_b32 v146, v146 offset:736
	ds_read_b32 v147, v147 offset:740
	ds_read_b32 v148, v148 offset:744
	ds_read_b32 v149, v149 offset:748
	ds_read_b32 v150, v150 offset:640
	ds_read_b32 v151, v151 offset:644
	ds_read_b32 v152, v152 offset:648
	ds_read_b32 v153, v153 offset:652
	ds_read_b32 v154, v154 offset:672
	ds_read_b32 v155, v155 offset:676
	ds_read_b32 v156, v156 offset:680
	ds_read_b32 v157, v157 offset:684
	s_waitcnt lgkmcnt(0)
	v_pk_add_f32 v[78:79], v[78:79], v[148:149]
	v_pk_add_f32 v[76:77], v[76:77], v[146:147]
	v_pk_add_f32 v[74:75], v[74:75], v[144:145]
	v_pk_add_f32 v[72:73], v[72:73], v[142:143]
	v_pk_add_f32 v[70:71], v[70:71], v[156:157]
	v_pk_add_f32 v[68:69], v[68:69], v[154:155]
	v_pk_add_f32 v[66:67], v[66:67], v[152:153]
	v_pk_add_f32 v[64:65], v[64:65], v[150:151]
.LBB0_74:
	s_waitcnt lgkmcnt(13)
	v_mfma_f32_32x32x16_bf16 v[0:15], v[162:165], v[220:223], v[0:15]
	ds_read_b64_tr_b16 v[162:163], v242 offset:0
	ds_read_b64_tr_b16 v[164:165], v242 offset:2048
	s_waitcnt lgkmcnt(8)
	v_mfma_f32_32x32x16_bf16 v[48:63], v[178:181], v[220:223], v[48:63]
	ds_read_b64_tr_b16 v[178:179], v243 offset:0
	ds_read_b64_tr_b16 v[180:181], v243 offset:2048
	v_max_i32_e32 v142, v80, v64
	v_max3_i32 v142, v142, v81, v65
	v_max3_i32 v142, v142, v82, v66
	v_max3_i32 v142, v142, v83, v67
	v_max3_i32 v142, v142, v84, v68
	v_max3_i32 v142, v142, v85, v69
	v_exp_f32_e32 v144, v82
	s_waitcnt lgkmcnt(13)
	v_mfma_f32_32x32x16_bf16 v[0:15], v[166:169], v[216:219], v[0:15]
	ds_read_b64_tr_b16 v[166:167], v242 offset:4096
	ds_read_b64_tr_b16 v[168:169], v242 offset:6144
	v_max3_i32 v142, v142, v86, v70
	v_max3_i32 v142, v142, v87, v71
	v_exp_f32_e32 v145, v66
	v_exp_f32_e32 v146, v88
	s_waitcnt lgkmcnt(10)
	v_mfma_f32_32x32x16_bf16 v[48:63], v[182:185], v[216:219], v[48:63]
	ds_read_b64_tr_b16 v[182:183], v243 offset:4096
	ds_read_b64_tr_b16 v[184:185], v243 offset:6144
	v_max3_i32 v142, v142, v88, v72
	v_max3_i32 v142, v142, v89, v73
	v_max3_i32 v142, v142, v90, v74
	v_exp_f32_e32 v147, v72
	s_waitcnt lgkmcnt(13)
	v_mfma_f32_32x32x16_bf16 v[0:15], v[170:173], v[212:215], v[0:15]
	ds_read_b64_tr_b16 v[170:171], v242 offset:8192
	ds_read_b64_tr_b16 v[172:173], v242 offset:10240
	v_max3_i32 v142, v142, v91, v75
	v_max3_i32 v142, v142, v92, v76
	v_max3_i32 v142, v142, v93, v77
	v_exp_f32_e32 v148, v90
	v_exp_f32_e32 v149, v74
	s_waitcnt lgkmcnt(12)
	v_mfma_f32_32x32x16_bf16 v[48:63], v[186:189], v[212:215], v[48:63]
	ds_read_b64_tr_b16 v[186:187], v243 offset:8192
	ds_read_b64_tr_b16 v[188:189], v243 offset:10240
	v_max3_i32 v142, v142, v94, v78
	v_max3_i32 v142, v142, v95, v79
	v_exp_f32_e32 v150, v92
	v_exp_f32_e32 v151, v76
	s_waitcnt lgkmcnt(13)
	v_mfma_f32_32x32x16_bf16 v[0:15], v[174:177], v[208:211], v[0:15]
	ds_read_b64_tr_b16 v[174:175], v242 offset:12288
	ds_read_b64_tr_b16 v[176:177], v242 offset:14336
	v_mov_b32_e32 v143, v142
	s_nop 1
	v_permlane32_swap_b32_e32 v142, v143
	v_exp_f32_e32 v152, v94
	s_waitcnt lgkmcnt(13)
	v_mfma_f32_32x32x16_bf16 v[48:63], v[200:203], v[208:211], v[48:63]
	ds_read_b64_tr_b16 v[200:201], v243 offset:12288
	ds_read_b64_tr_b16 v[202:203], v243 offset:14336
	v_max_i32_e32 v142, v142, v143
	s_mov_b32 s0, 0x41000000
	v_cmp_lt_i32_e32 vcc, s0, v142
	v_exp_f32_e32 v153, v78
	s_cbranch_vccz .Latt_fast
	s_waitcnt lgkmcnt(0)
	s_setprio 1
	v_mfma_f32_32x32x16_bf16 v[32:47], v[162:165], v[220:223], v[32:47]
	v_mfma_f32_32x32x16_bf16 v[16:31], v[178:181], v[220:223], v[16:31]
	v_mfma_f32_32x32x16_bf16 v[32:47], v[166:169], v[216:219], v[32:47]
	v_mfma_f32_32x32x16_bf16 v[16:31], v[182:185], v[216:219], v[16:31]
	v_mfma_f32_32x32x16_bf16 v[32:47], v[170:173], v[212:215], v[32:47]
	v_mfma_f32_32x32x16_bf16 v[16:31], v[186:189], v[212:215], v[16:31]
	v_mfma_f32_32x32x16_bf16 v[32:47], v[174:177], v[208:211], v[32:47]
	v_mfma_f32_32x32x16_bf16 v[16:31], v[200:203], v[208:211], v[16:31]
	s_setprio 0
	s_nop 15
	v_max_f32_e32 v142, v142, v142
	v_max_f32_e32 v142, 0, v142
	v_exp_f32_e64 v144, -v142
	v_sub_f32_e32 v95, v95, v142
	v_sub_f32_e32 v94, v94, v142
	v_sub_f32_e32 v93, v93, v142
	v_mov_b32_e32 v143, v144
	v_pk_mul_f32 v[14:15], v[14:15], v[144:145] op_sel_hi:[1,0]
	v_pk_mul_f32 v[12:13], v[12:13], v[144:145] op_sel_hi:[1,0]
	v_pk_mul_f32 v[10:11], v[10:11], v[144:145] op_sel_hi:[1,0]
	v_pk_mul_f32 v[8:9], v[8:9], v[144:145] op_sel_hi:[1,0]
	v_pk_mul_f32 v[6:7], v[6:7], v[144:145] op_sel_hi:[1,0]
	v_pk_mul_f32 v[4:5], v[4:5], v[144:145] op_sel_hi:[1,0]
	v_pk_mul_f32 v[2:3], v[2:3], v[144:145] op_sel_hi:[1,0]
	v_pk_mul_f32 v[0:1], v[0:1], v[144:145] op_sel_hi:[1,0]
	v_pk_mul_f32 v[62:63], v[62:63], v[144:145] op_sel_hi:[1,0]
	v_pk_mul_f32 v[60:61], v[60:61], v[144:145] op_sel_hi:[1,0]
	v_pk_mul_f32 v[58:59], v[58:59], v[144:145] op_sel_hi:[1,0]
	v_pk_mul_f32 v[56:57], v[56:57], v[144:145] op_sel_hi:[1,0]
	v_pk_mul_f32 v[54:55], v[54:55], v[144:145] op_sel_hi:[1,0]
	v_pk_mul_f32 v[52:53], v[52:53], v[144:145] op_sel_hi:[1,0]
	v_pk_mul_f32 v[50:51], v[50:51], v[144:145] op_sel_hi:[1,0]
	v_pk_mul_f32 v[48:49], v[48:49], v[144:145] op_sel_hi:[1,0]
	v_pk_mul_f32 v[46:47], v[46:47], v[144:145] op_sel_hi:[1,0]
	v_pk_mul_f32 v[44:45], v[44:45], v[144:145] op_sel_hi:[1,0]
	v_pk_mul_f32 v[42:43], v[42:43], v[144:145] op_sel_hi:[1,0]
	v_pk_mul_f32 v[40:41], v[40:41], v[144:145] op_sel_hi:[1,0]
	v_pk_mul_f32 v[38:39], v[38:39], v[144:145] op_sel_hi:[1,0]
	v_pk_mul_f32 v[36:37], v[36:37], v[144:145] op_sel_hi:[1,0]
	v_pk_mul_f32 v[34:35], v[34:35], v[144:145] op_sel_hi:[1,0]
	v_pk_mul_f32 v[32:33], v[32:33], v[144:145] op_sel_hi:[1,0]
	v_pk_mul_f32 v[30:31], v[30:31], v[144:145] op_sel_hi:[1,0]
	v_pk_mul_f32 v[28:29], v[28:29], v[144:145] op_sel_hi:[1,0]
	v_pk_mul_f32 v[26:27], v[26:27], v[144:145] op_sel_hi:[1,0]
	v_pk_mul_f32 v[24:25], v[24:25], v[144:145] op_sel_hi:[1,0]
	v_pk_mul_f32 v[22:23], v[22:23], v[144:145] op_sel_hi:[1,0]
	v_pk_mul_f32 v[20:21], v[20:21], v[144:145] op_sel_hi:[1,0]
	v_pk_mul_f32 v[18:19], v[18:19], v[144:145] op_sel_hi:[1,0]
	v_pk_mul_f32 v[16:17], v[16:17], v[144:145] op_sel_hi:[1,0]
	v_pk_add_f32 v[144:145], v[124:125], v[142:143]
	v_pk_mul_f32 v[124:125], v[124:125], v[142:143]
	v_sub_f32_e32 v92, v92, v142
	v_mov_b32_e32 v145, v125
	v_sub_f32_e32 v91, v91, v142
	v_sub_f32_e32 v90, v90, v142
	v_sub_f32_e32 v89, v89, v142
	v_sub_f32_e32 v88, v88, v142
	v_sub_f32_e32 v87, v87, v142
	v_sub_f32_e32 v86, v86, v142
	v_sub_f32_e32 v85, v85, v142
	v_sub_f32_e32 v84, v84, v142
	v_sub_f32_e32 v83, v83, v142
	v_sub_f32_e32 v82, v82, v142
	v_sub_f32_e32 v81, v81, v142
	v_sub_f32_e32 v80, v80, v142
	v_sub_f32_e32 v79, v79, v142
	v_sub_f32_e32 v78, v78, v142
	v_sub_f32_e32 v77, v77, v142
	v_sub_f32_e32 v76, v76, v142
	v_sub_f32_e32 v75, v75, v142
	v_sub_f32_e32 v74, v74, v142
	v_sub_f32_e32 v73, v73, v142
	v_sub_f32_e32 v72, v72, v142
	v_sub_f32_e32 v71, v71, v142
	v_sub_f32_e32 v70, v70, v142
	v_sub_f32_e32 v69, v69, v142
	v_sub_f32_e32 v68, v68, v142
	v_sub_f32_e32 v67, v67, v142
	v_sub_f32_e32 v66, v66, v142
	v_sub_f32_e32 v65, v65, v142
	v_sub_f32_e32 v64, v64, v142
	v_mov_b64_e32 v[124:125], v[144:145]
	v_exp_f32_e32 v142, v80
	v_exp_f32_e32 v143, v64
	v_exp_f32_e32 v64, v81
	v_exp_f32_e32 v65, v65
	v_exp_f32_e32 v144, v82
	v_exp_f32_e32 v145, v66
	v_exp_f32_e32 v66, v83
	v_exp_f32_e32 v67, v67
	v_pk_add_f32 v[80:81], v[142:143], 0 op_sel_hi:[1,0]
	v_exp_f32_e32 v82, v84
	v_exp_f32_e32 v83, v68
	v_pk_add_f32 v[80:81], v[64:65], v[80:81]
	v_exp_f32_e32 v68, v85
	v_exp_f32_e32 v69, v69
	v_pk_add_f32 v[80:81], v[144:145], v[80:81]
	v_exp_f32_e32 v84, v86
	v_exp_f32_e32 v85, v70
	v_pk_add_f32 v[80:81], v[66:67], v[80:81]
	v_exp_f32_e32 v86, v87
	v_exp_f32_e32 v87, v71
	v_pk_add_f32 v[70:71], v[82:83], v[80:81]
	v_exp_f32_e32 v146, v88
	v_exp_f32_e32 v147, v72
	v_pk_add_f32 v[70:71], v[68:69], v[70:71]
	v_exp_f32_e32 v88, v89
	v_exp_f32_e32 v89, v73
	v_pk_add_f32 v[70:71], v[84:85], v[70:71]
	v_exp_f32_e32 v148, v90
	v_exp_f32_e32 v149, v74
	v_pk_add_f32 v[70:71], v[86:87], v[70:71]
	v_exp_f32_e32 v90, v91
	v_exp_f32_e32 v91, v75
	v_pk_add_f32 v[70:71], v[146:147], v[70:71]
	v_exp_f32_e32 v150, v92
	v_exp_f32_e32 v151, v76
	v_pk_add_f32 v[70:71], v[88:89], v[70:71]
	v_exp_f32_e32 v92, v93
	v_exp_f32_e32 v93, v77
	v_pk_add_f32 v[70:71], v[148:149], v[70:71]
	v_exp_f32_e32 v152, v94
	v_exp_f32_e32 v153, v78
	v_pk_add_f32 v[70:71], v[90:91], v[70:71]
	v_exp_f32_e32 v94, v95
	v_exp_f32_e32 v95, v79
	v_pk_add_f32 v[70:71], v[150:151], v[70:71]
	s_branch .Latt_tail
.Latt_fast:
	s_waitcnt lgkmcnt(13)
	v_mfma_f32_32x32x16_bf16 v[32:47], v[162:165], v[220:223], v[32:47]
	v_exp_f32_e32 v142, v80
	v_exp_f32_e32 v143, v64
	v_exp_f32_e32 v64, v81
	v_exp_f32_e32 v65, v65
	v_exp_f32_e32 v66, v83
	s_waitcnt lgkmcnt(12)
	v_mfma_f32_32x32x16_bf16 v[16:31], v[178:181], v[220:223], v[16:31]
	v_exp_f32_e32 v67, v67
	v_pk_add_f32 v[80:81], v[142:143], 0 op_sel_hi:[1,0]
	v_exp_f32_e32 v82, v84
	v_exp_f32_e32 v83, v68
	v_pk_add_f32 v[80:81], v[64:65], v[80:81]
	s_waitcnt lgkmcnt(10)
	v_mfma_f32_32x32x16_bf16 v[32:47], v[166:169], v[216:219], v[32:47]
	v_exp_f32_e32 v68, v85
	v_exp_f32_e32 v69, v69
	v_pk_add_f32 v[80:81], v[144:145], v[80:81]
	v_exp_f32_e32 v84, v86
	v_exp_f32_e32 v85, v70
	s_waitcnt lgkmcnt(8)
	v_mfma_f32_32x32x16_bf16 v[16:31], v[182:185], v[216:219], v[16:31]
	v_pk_add_f32 v[80:81], v[66:67], v[80:81]
	v_exp_f32_e32 v86, v87
	v_exp_f32_e32 v87, v71
	v_pk_add_f32 v[70:71], v[82:83], v[80:81]
	s_waitcnt lgkmcnt(6)
	v_mfma_f32_32x32x16_bf16 v[32:47], v[170:173], v[212:215], v[32:47]
	v_pk_add_f32 v[70:71], v[68:69], v[70:71]
	v_exp_f32_e32 v88, v89
	v_exp_f32_e32 v89, v73
	v_pk_add_f32 v[70:71], v[84:85], v[70:71]
	s_waitcnt lgkmcnt(4)
	v_mfma_f32_32x32x16_bf16 v[16:31], v[186:189], v[212:215], v[16:31]
	v_pk_add_f32 v[70:71], v[86:87], v[70:71]
	v_exp_f32_e32 v90, v91
	v_exp_f32_e32 v91, v75
	v_pk_add_f32 v[70:71], v[146:147], v[70:71]
	s_waitcnt lgkmcnt(2)
	v_mfma_f32_32x32x16_bf16 v[32:47], v[174:177], v[208:211], v[32:47]
	v_pk_add_f32 v[70:71], v[88:89], v[70:71]
	v_exp_f32_e32 v92, v93
	v_exp_f32_e32 v93, v77
	v_pk_add_f32 v[70:71], v[148:149], v[70:71]
	s_waitcnt lgkmcnt(0)
	v_mfma_f32_32x32x16_bf16 v[16:31], v[200:203], v[208:211], v[16:31]
	v_pk_add_f32 v[70:71], v[90:91], v[70:71]
	v_exp_f32_e32 v94, v95
	v_exp_f32_e32 v95, v79
	v_pk_add_f32 v[70:71], v[150:151], v[70:71]
